# retention state scan: the idle score-GEMM workgroups (same XCD) touch the next chunks' K^T / V^T operands ahead of their scan partner (paced cache warm-up, results discarded)
# baseline (speedup 1.0000x reference)
; __device__ __forceinline__ float ex2(float x) { return __builtin_amdgcn_exp2f(x); }
; #define EPI_ROWS(ai, m) _Pragma("unroll") for (int ai = 0; ai < 2; ++ai) _Pragma("unroll") for (int m = 0; m < 4; ++m)
; __device__ __forceinline__ u32x4 pk8(f32x4 a, f32x4 b) { const u32x2 x = pk4(a), y = pk4(b); return (u32x4){x.x, x.y, y.x, y.y}; }
;     __device__ __forceinline__ float carry_scale(const Unit& u) const { const int hd = u.pn >> 1, h = hd >> 1, dir = hd & 1; return ex2(256.f * ret_log2g(dir ? 7 - h : h)); }
;     __device__ __forceinline__ void operator()(const Acc& acc, const Unit& u, int wr, int wc, int fr, int fq) const {
;         const int half = u.pn & 1, hd = u.pn >> 1, h = hd >> 1, dir = hd & 1, sq = u.aux; const int b = u.pm >= 32 ? u.pm - 32 : (u.pm >> 3);
;         if (sq < 8) { const int pmn = ret_chunk(sq + 1, b, dir); bf16_t* base = B3 + (((size_t)pmn * 8 + h) * 512 + half * 256) * 768 + dir * 256;
;             EPI_ROWS(ai, m) { const int r = ai * 128 + wr * 64 + m * 16 + fr;
; #pragma unroll
;                 for (int bj = 0; bj < 2; ++bj) { const int c = bj * 128 + wc * 32 + fq * 8; *(u32x4*)(base + (size_t)r * 768 + c) = pk8(acc[ai][bj][m][0], acc[ai][bj][m][1]); } } }
;         if (sq == 0) { bf16_t* base = B3 + (((size_t)u.pm * 8 + h) * 512 + half * 256) * 768 + dir * 256;
;             EPI_ROWS(ai, m) { const int r = ai * 128 + wr * 64 + m * 16 + fr;
; #pragma unroll
;                 for (int bj = 0; bj < 2; ++bj) { const int c = bj * 128 + wc * 32 + fq * 8; *(u32x4*)(base + (size_t)r * 768 + c) = (u32x4){0u, 0u, 0u, 0u}; } } }
;     }
;         u.pm = ret_chunk(i, b, dir); u.pn = (((h * 2 + dir) << 1) | half); u.nt = 4; u.aux = i; map(u); return true; }
.LBB0_612:
	s_sub_i32 s14, s96, 0x80
	s_and_b32 s15, s14, 7
	s_lshl_b32 s15, s15, 4
	s_lshr_b32 s14, s14, 3
	s_or_b32 s14, s14, s15
	s_and_b32 s15, s14, 1
	s_bfe_u32 s16, s14, 0x10001
	s_bfe_u32 s17, s14, 0x30002
	s_lshr_b32 s18, s14, 5
	s_lshl_b32 s19, s18, 3
	s_cmp_eq_u32 s16, 0
	s_cselect_b32 s20, 3, 4
	s_add_i32 s19, s19, s20
	s_lshl_b32 s19, s19, 3
	s_add_i32 s19, s19, s17
	s_mul_i32 s20, s19, 0xc0000
	s_mul_i32 s22, s15, 0x60000
	s_add_i32 s20, s20, s22
	s_add_i32 s20, s20, 0x34b00400
	s_lshl_b32 s22, s19, 17
	s_cmp_eq_u32 s16, 0
	s_mov_b32 s23, 0x2bb00000
	s_cselect_b32 s23, 0x29700000, s23
	s_add_i32 s22, s22, s23
	v_lshrrev_b32_e32 v46, 1, v141
	v_mul_u32_u24_e32 v46, 0x600, v46
	v_and_b32_e32 v47, 1, v141
	v_lshl_add_u32 v46, v47, 8, v46
	v_add_u32_e32 v46, s20, v46
	v_lshlrev_b32_e32 v47, 8, v141
	v_add_u32_e32 v47, s22, v47
	s_cmp_eq_u32 s16, 0
	s_mov_b32 s14, 0xffa00000
	s_mov_b32 s15, 0xfff00000
	s_cselect_b32 s14, 0x600000, s14
	s_cselect_b32 s15, 0x100000, s15
	s_mov_b32 s8, 5
.Lkvpf_loop:
	global_load_dword v50, v46, s[4:5]
	global_load_dword v51, v46, s[4:5] offset:128
	global_load_dword v52, v47, s[4:5]
	global_load_dword v53, v47, s[4:5] offset:128
	v_add_u32_e32 v46, s14, v46
	v_add_u32_e32 v47, s15, v47
	s_waitcnt vmcnt(0)
	s_sleep 127
	s_sleep 127
	s_sub_i32 s8, s8, 1
	s_cmp_lg_u32 s8, 0
	s_cbranch_scc1 .Lkvpf_loop
	s_mov_b64 s[2:3], 0
